# v21: v20 + write-through (sc1) stores in the combined input projection epilogue (q,k,v,xa,xl,gg)
# speedup vs baseline: 1.0082x; 1.0027x over previous
; __device__ __forceinline__ float fgelu_tanh(float v) { return v * fsig(1.5957691216057308f * (v + 0.044715f * v * v * v)); }
; __device__ __forceinline__ u32x4 pack8(const f32x4 v0, const f32x4 v1) { u32x4 w; w.x = cvt_pk_bf16(v0[0], v0[1]); w.y = cvt_pk_bf16(v0[2], v0[3]); w.z = cvt_pk_bf16(v1[0], v1[1]); w.w = cvt_pk_bf16(v1[2], v1[3]); return w; }
; __device__ __forceinline__ void rstd8(const float* ss, int row0, float sc, float (&rs)[2][4]) {
;     ...
;         for (int m = 0; m < 4; ++m) pa[ai][m] = *(const f32x4*)(ss + (size_t)(row0 + ai * HALF + m * 16) * 4);
; #pragma unroll
;     for (int ai = 0; ai < 2; ++ai)
; #pragma unroll
;         for (int m = 0; m < 4; ++m) { const f32x4 a = pa[ai][m]; rs[ai][m] = rsqrtf(((a[0] + a[1]) + (a[2] + a[3])) * (1.0f / 1024.0f) + 1e-6f) * sc; }
;     __device__ __forceinline__ void operator()(const f32x4 (&acc)[2][2][4][2], const Unit& u, int wr, int wc, int fr, int fq) const {
;     ...
;             for (int m = 0; m < 4; ++m) { const int row = row0 + ai * HALF + m * 16; const float rs = rsv[ai][m];
; #pragma unroll
;                 for (int bj = 0; bj < 2; ++bj) { f32x4 v0 = acc[ai][bj][m][0] * rs, v1 = acc[ai][bj][m][1] * rs;
;                     if (act) {
; #pragma unroll
;                         for (int i = 0; i < 4; ++i) { v0[i] = fgelu_tanh(v0[i]); v1[i] = fgelu_tanh(v1[i]); } }
;                     *(u32x4*)(dst + (size_t)row * ld + col0 + bj * HALF) = pack8(v0, v1); __builtin_amdgcn_sched_barrier(0); } }
.LBB0_525:
	v_lshl_or_b32 v146, s18, 8, v192
	v_ashrrev_i32_e32 v147, 31, v146
	v_lshl_add_u64 v[146:147], v[146:147], 1, s[8:9]
	v_mul_lo_u32 v181, s45, v182
	v_mul_lo_u32 v183, s44, v183
	v_mad_u64_u32 v[148:149], s[8:9], s44, v182, 0
	v_add3_u32 v149, v149, v183, v181
	s_movk_i32 s70, 0x100
	s_mov_b32 s71, 0xbfb8aa3b
	v_lshl_add_u64 v[148:149], v[148:149], 1, v[146:147]
	v_mov_b32_e32 v185, v184
	v_cvt_pk_bf16_f32 v186, v186, v187
	v_cvt_pk_bf16_f32 v187, v152, v153
	v_cvt_pk_bf16_f32 v188, v188, v189
	v_cvt_pk_bf16_f32 v189, v150, v151
	global_store_dwordx4 v[148:149], v[186:189], off sc1
	v_mov_b32_e32 v150, v184
	v_mov_b32_e32 v151, v184
	v_pk_mul_f32 v[136:137], v[136:137], v[150:151]
	v_pk_mul_f32 v[134:135], v[134:135], v[184:185]
	v_pk_mul_f32 v[132:133], v[132:133], v[150:151]
	s_and_b64 vcc, exec, s[4:5]
	v_pk_mul_f32 v[130:131], v[130:131], v[184:185]
	s_cbranch_vccnz .LBB0_527
	v_mul_f32_e32 v151, 0x3d372713, v130
	v_mul_f32_e32 v151, v130, v151
	v_fma_f32 v151, v130, v151, v130
	v_mul_f32_e32 v151, 0x3fcc422a, v151
	v_mul_f32_e32 v151, 0xbfb8aa3b, v151
	v_exp_f32_e32 v151, v151
	v_mov_b32_e32 v153, v135
	v_mov_b32_e32 v181, v131
	v_mul_f32_e32 v150, 0x3d372713, v134
	v_add_f32_e32 v151, 1.0, v151
	v_rcp_f32_e32 v152, v151
	v_mul_f32_e32 v151, 0x3d372713, v135
	v_mul_f32_e32 v151, v135, v151
	v_fmac_f32_e32 v153, v153, v151
	v_mul_f32_e32 v151, 0x3fcc422a, v153
	v_mul_f32_e32 v153, 0x3d372713, v131
	v_mul_f32_e32 v153, v131, v153
	v_fmac_f32_e32 v181, v181, v153
	v_mul_f32_e32 v153, 0x3fcc422a, v181
	v_mul_f32_e32 v181, 0x3d372713, v136
	v_mul_f32_e32 v181, v136, v181
	v_fma_f32 v181, v136, v181, v136
	v_mul_f32_e32 v181, 0x3fcc422a, v181
	v_mul_f32_e32 v181, 0xbfb8aa3b, v181
	v_exp_f32_e32 v181, v181
	v_mul_f32_e32 v150, v134, v150
	v_fma_f32 v150, v134, v150, v134
	v_mul_f32_e32 v150, 0x3fcc422a, v150
	v_add_f32_e32 v181, 1.0, v181
	v_mul_f32_e32 v150, 0xbfb8aa3b, v150
	v_mul_f32_e32 v151, 0xbfb8aa3b, v151
	v_rcp_f32_e32 v182, v181
	v_mul_f32_e32 v181, 0x3d372713, v132
	v_exp_f32_e32 v150, v150
	v_exp_f32_e32 v151, v151
	v_mul_f32_e32 v181, v132, v181
	v_fma_f32 v181, v132, v181, v132
	v_mul_f32_e32 v181, 0x3fcc422a, v181
	v_mul_f32_e32 v181, 0xbfb8aa3b, v181
	v_add_f32_e32 v150, 1.0, v150
	v_add_f32_e32 v151, 1.0, v151
	v_exp_f32_e32 v181, v181
	v_rcp_f32_e32 v150, v150
	v_rcp_f32_e32 v151, v151
	v_mul_f32_e32 v153, 0xbfb8aa3b, v153
	v_add_f32_e32 v181, 1.0, v181
	v_rcp_f32_e32 v184, v181
	v_mul_f32_e32 v181, 0x3d372713, v137
	v_pk_mul_f32 v[134:135], v[134:135], v[150:151]
	v_mul_f32_e32 v150, 0x3d372713, v133
	v_mul_f32_e32 v181, v137, v181
	v_mul_f32_e32 v150, v133, v150
	v_fma_f32 v181, v137, v181, v137
	v_fma_f32 v150, v133, v150, v133
	v_mul_f32_e32 v181, 0x3fcc422a, v181
	v_mul_f32_e32 v150, 0x3fcc422a, v150
	v_mul_f32_e32 v181, 0xbfb8aa3b, v181
	v_mul_f32_e32 v150, 0xbfb8aa3b, v150
	v_exp_f32_e32 v153, v153
	v_exp_f32_e32 v181, v181
	v_exp_f32_e32 v150, v150
	v_add_f32_e32 v153, 1.0, v153
	v_add_f32_e32 v181, 1.0, v181
	v_add_f32_e32 v150, 1.0, v150
	v_rcp_f32_e32 v153, v153
	v_rcp_f32_e32 v183, v181
	v_rcp_f32_e32 v185, v150
	v_pk_mul_f32 v[130:131], v[130:131], v[152:153]
	v_pk_mul_f32 v[136:137], v[136:137], v[182:183]
	v_pk_mul_f32 v[132:133], v[132:133], v[184:185]
.LBB0_527:
	v_mul_f32_e32 v150, 0x4b800000, v180
	v_cndmask_b32_e64 v150, v180, v150, s[6:7]
	v_rsq_f32_e32 v150, v150
	v_cvt_pk_bf16_f32 v134, v134, v135
	v_cvt_pk_bf16_f32 v135, v136, v137
	v_cvt_pk_bf16_f32 v136, v130, v131
	v_cvt_pk_bf16_f32 v137, v132, v133
	global_store_dwordx4 v[148:149], v[134:137], off offset:256 sc1
	v_mul_f32_e32 v130, 0x45800000, v150
	v_cndmask_b32_e64 v130, v150, v130, s[6:7]
	v_mul_f32_e32 v130, s17, v130
	v_pk_mul_f32 v[128:129], v[128:129], v[130:131] op_sel_hi:[1,0]
	v_pk_mul_f32 v[126:127], v[126:127], v[130:131] op_sel_hi:[1,0]
	v_pk_mul_f32 v[124:125], v[124:125], v[130:131] op_sel_hi:[1,0]
	s_and_b64 vcc, exec, s[4:5]
	v_pk_mul_f32 v[132:133], v[122:123], v[130:131] op_sel_hi:[1,0]
	s_cbranch_vccnz .LBB0_529
	v_mul_f32_e32 v123, 0x3d372713, v132
	v_mul_f32_e32 v123, v132, v123
	v_fma_f32 v123, v132, v123, v132
	v_mul_f32_e32 v123, 0x3fcc422a, v123
	v_mul_f32_e32 v123, 0xbfb8aa3b, v123
	v_exp_f32_e32 v123, v123
	v_mov_b32_e32 v131, v127
	v_mov_b32_e32 v135, v133
	v_mul_f32_e32 v122, 0x3d372713, v126
	v_add_f32_e32 v123, 1.0, v123
	v_rcp_f32_e32 v134, v123
	v_mul_f32_e32 v123, 0x3d372713, v127
	v_mul_f32_e32 v123, v127, v123
	v_fmac_f32_e32 v131, v131, v123
	v_mul_f32_e32 v123, 0x3fcc422a, v131
	v_mul_f32_e32 v131, 0x3d372713, v133
	v_mul_f32_e32 v131, v133, v131
	v_fmac_f32_e32 v135, v135, v131
	v_mul_f32_e32 v131, 0x3fcc422a, v135
	v_mul_f32_e32 v131, 0xbfb8aa3b, v131
	v_exp_f32_e32 v131, v131
	v_mul_f32_e32 v122, v126, v122
	v_fma_f32 v122, v126, v122, v126
	v_mul_f32_e32 v122, 0x3fcc422a, v122
	v_add_f32_e32 v131, 1.0, v131
	v_rcp_f32_e32 v135, v131
	v_mul_f32_e32 v131, 0x3d372713, v128
	v_mul_f32_e32 v131, v128, v131
	v_fma_f32 v131, v128, v131, v128
	v_mul_f32_e32 v131, 0x3fcc422a, v131
	v_mul_f32_e32 v131, 0xbfb8aa3b, v131
	v_exp_f32_e32 v131, v131
	v_mul_f32_e32 v122, 0xbfb8aa3b, v122
	v_mul_f32_e32 v123, 0xbfb8aa3b, v123
	v_exp_f32_e32 v122, v122
	v_add_f32_e32 v131, 1.0, v131
	v_rcp_f32_e32 v136, v131
	v_mul_f32_e32 v131, 0x3d372713, v124
	v_exp_f32_e32 v123, v123
	v_mul_f32_e32 v131, v124, v131
	v_fma_f32 v131, v124, v131, v124
	v_mul_f32_e32 v131, 0x3fcc422a, v131
	v_mul_f32_e32 v131, 0xbfb8aa3b, v131
	v_add_f32_e32 v122, 1.0, v122
	v_add_f32_e32 v123, 1.0, v123
	v_exp_f32_e32 v131, v131
	v_rcp_f32_e32 v122, v122
	v_rcp_f32_e32 v123, v123
	v_pk_mul_f32 v[132:133], v[132:133], v[134:135]
	v_add_f32_e32 v131, 1.0, v131
	v_rcp_f32_e32 v148, v131
	v_mul_f32_e32 v131, 0x3d372713, v129
	v_pk_mul_f32 v[126:127], v[126:127], v[122:123]
	v_mul_f32_e32 v122, 0x3d372713, v125
	v_mul_f32_e32 v131, v129, v131
	v_mul_f32_e32 v122, v125, v122
	v_fma_f32 v131, v129, v131, v129
	v_fma_f32 v122, v125, v122, v125
	v_mul_f32_e32 v131, 0x3fcc422a, v131
	v_mul_f32_e32 v122, 0x3fcc422a, v122
	v_mul_f32_e32 v131, 0xbfb8aa3b, v131
	v_mul_f32_e32 v122, 0xbfb8aa3b, v122
	v_exp_f32_e32 v131, v131
	v_exp_f32_e32 v122, v122
	v_add_f32_e32 v131, 1.0, v131
	v_add_f32_e32 v122, 1.0, v122
	v_rcp_f32_e32 v137, v131
	v_rcp_f32_e32 v149, v122
	v_pk_mul_f32 v[128:129], v[128:129], v[136:137]
	v_pk_mul_f32 v[124:125], v[124:125], v[148:149]
; __device__ __forceinline__ float fgelu_tanh(float v) { return v * fsig(1.5957691216057308f * (v + 0.044715f * v * v * v)); }
; __device__ __forceinline__ u32x4 pack8(const f32x4 v0, const f32x4 v1) { u32x4 w; w.x = cvt_pk_bf16(v0[0], v0[1]); w.y = cvt_pk_bf16(v0[2], v0[3]); w.z = cvt_pk_bf16(v1[0], v1[1]); w.w = cvt_pk_bf16(v1[2], v1[3]); return w; }
; __device__ __forceinline__ void rstd8(const float* ss, int row0, float sc, float (&rs)[2][4]) {
;     ...
;         for (int m = 0; m < 4; ++m) pa[ai][m] = *(const f32x4*)(ss + (size_t)(row0 + ai * HALF + m * 16) * 4);
; #pragma unroll
;     for (int ai = 0; ai < 2; ++ai)
; #pragma unroll
;         for (int m = 0; m < 4; ++m) { const f32x4 a = pa[ai][m]; rs[ai][m] = rsqrtf(((a[0] + a[1]) + (a[2] + a[3])) * (1.0f / 1024.0f) + 1e-6f) * sc; }
;     __device__ __forceinline__ void operator()(const f32x4 (&acc)[2][2][4][2], const Unit& u, int wr, int wc, int fr, int fq) const {
;     ...
;             for (int m = 0; m < 4; ++m) { const int row = row0 + ai * HALF + m * 16; const float rs = rsv[ai][m];
; #pragma unroll
;                 for (int bj = 0; bj < 2; ++bj) { f32x4 v0 = acc[ai][bj][m][0] * rs, v1 = acc[ai][bj][m][1] * rs;
;                     if (act) {
; #pragma unroll
;                         for (int i = 0; i < 4; ++i) { v0[i] = fgelu_tanh(v0[i]); v1[i] = fgelu_tanh(v1[i]); } }
;                     *(u32x4*)(dst + (size_t)row * ld + col0 + bj * HALF) = pack8(v0, v1); __builtin_amdgcn_sched_barrier(0); } }
.LBB0_529:
	v_mul_lo_u32 v134, s45, v178
	v_mul_lo_u32 v135, s44, v179
	v_mad_u64_u32 v[122:123], s[6:7], s44, v178, 0
	v_add3_u32 v123, v123, v135, v134
	v_lshl_add_u64 v[122:123], v[122:123], 1, v[146:147]
	v_mov_b32_e32 v131, v130
	v_cvt_pk_bf16_f32 v126, v126, v127
	v_cvt_pk_bf16_f32 v127, v128, v129
	v_cvt_pk_bf16_f32 v128, v132, v133
	v_cvt_pk_bf16_f32 v129, v124, v125
	global_store_dwordx4 v[122:123], v[126:129], off sc1
	s_nop 1
	v_mov_b32_e32 v126, v130
	v_mov_b32_e32 v127, v130
	v_pk_mul_f32 v[120:121], v[120:121], v[126:127]
	v_pk_mul_f32 v[124:125], v[118:119], v[130:131]
	v_pk_mul_f32 v[118:119], v[116:117], v[126:127]
	s_and_b64 vcc, exec, s[4:5]
	v_pk_mul_f32 v[126:127], v[114:115], v[130:131]
	s_cbranch_vccnz .LBB0_531
	v_mul_f32_e32 v115, 0x3d372713, v126
	v_mul_f32_e32 v115, v126, v115
	v_fma_f32 v115, v126, v115, v126
	v_mul_f32_e32 v115, 0x3fcc422a, v115
	v_mul_f32_e32 v115, 0xbfb8aa3b, v115
	v_exp_f32_e32 v115, v115
	v_mul_f32_e32 v114, 0x3d372713, v124
	v_mul_f32_e32 v114, v124, v114
	v_mov_b32_e32 v117, v125
	v_add_f32_e32 v115, 1.0, v115
	v_rcp_f32_e32 v116, v115
	v_mul_f32_e32 v115, 0x3d372713, v125
	v_mul_f32_e32 v115, v125, v115
	v_fma_f32 v114, v124, v114, v124
	v_fmac_f32_e32 v117, v117, v115
	v_mul_f32_e32 v114, 0x3fcc422a, v114
	v_mul_f32_e32 v115, 0x3fcc422a, v117
	v_mul_f32_e32 v114, 0xbfb8aa3b, v114
	v_mul_f32_e32 v115, 0xbfb8aa3b, v115
	v_mul_f32_e32 v129, 0x3d372713, v118
	v_exp_f32_e32 v114, v114
	v_exp_f32_e32 v115, v115
	v_mul_f32_e32 v129, v118, v129
	v_fma_f32 v129, v118, v129, v118
	v_mul_f32_e32 v129, 0x3fcc422a, v129
	v_mul_f32_e32 v129, 0xbfb8aa3b, v129
	v_add_f32_e32 v114, 1.0, v114
	v_add_f32_e32 v115, 1.0, v115
	v_exp_f32_e32 v129, v129
	v_rcp_f32_e32 v114, v114
	v_rcp_f32_e32 v115, v115
	v_mul_f32_e32 v117, 0x3d372713, v127
	v_mul_f32_e32 v117, v127, v117
	v_mov_b32_e32 v128, v127
	v_fmac_f32_e32 v128, v128, v117
	v_add_f32_e32 v129, 1.0, v129
	v_mul_f32_e32 v117, 0x3fcc422a, v128
	v_mul_f32_e32 v128, 0x3d372713, v120
	v_rcp_f32_e32 v130, v129
	v_mul_f32_e32 v129, 0x3d372713, v121
	v_pk_mul_f32 v[124:125], v[124:125], v[114:115]
	v_mul_f32_e32 v114, 0x3d372713, v119
	v_mul_f32_e32 v128, v120, v128
	v_mul_f32_e32 v129, v121, v129
	v_mul_f32_e32 v114, v119, v114
	v_fma_f32 v128, v120, v128, v120
	v_fma_f32 v129, v121, v129, v121
	v_fma_f32 v114, v119, v114, v119
	v_mul_f32_e32 v128, 0x3fcc422a, v128
	v_mul_f32_e32 v129, 0x3fcc422a, v129
	v_mul_f32_e32 v114, 0x3fcc422a, v114
	v_mul_f32_e32 v117, 0xbfb8aa3b, v117
	v_mul_f32_e32 v128, 0xbfb8aa3b, v128
	v_mul_f32_e32 v129, 0xbfb8aa3b, v129
	v_mul_f32_e32 v114, 0xbfb8aa3b, v114
	v_exp_f32_e32 v117, v117
	v_exp_f32_e32 v128, v128
	v_exp_f32_e32 v129, v129
	v_exp_f32_e32 v114, v114
	v_add_f32_e32 v117, 1.0, v117
	v_add_f32_e32 v128, 1.0, v128
	v_add_f32_e32 v129, 1.0, v129
	v_add_f32_e32 v114, 1.0, v114
	v_rcp_f32_e32 v117, v117
	v_rcp_f32_e32 v128, v128
	v_rcp_f32_e32 v129, v129
	v_rcp_f32_e32 v131, v114
	v_pk_mul_f32 v[126:127], v[126:127], v[116:117]
	v_pk_mul_f32 v[120:121], v[120:121], v[128:129]
	v_pk_mul_f32 v[118:119], v[118:119], v[130:131]
.LBB0_531:
	v_mov_b32_e32 v114, v143
	v_mov_b32_e32 v115, v144
	v_mov_b32_e32 v143, v145
	v_mov_b32_e32 v116, v139
	v_mov_b32_e32 v117, v140
	v_mov_b32_e32 v139, v141
	v_pk_add_f32 v[114:115], v[114:115], v[142:143]
	v_pk_add_f32 v[116:117], v[116:117], v[138:139]
	v_mov_b32_e32 v129, v114
	v_mov_b32_e32 v128, v116
	v_mov_b32_e32 v114, v117
	v_pk_add_f32 v[114:115], v[128:129], v[114:115]
	v_cvt_pk_bf16_f32 v124, v124, v125
	v_cvt_pk_bf16_f32 v125, v120, v121
	v_cvt_pk_bf16_f32 v126, v126, v127
	v_cvt_pk_bf16_f32 v127, v118, v119
	global_store_dwordx4 v[122:123], v[124:127], off offset:256 sc1
	v_pk_fma_f32 v[114:115], v[114:115], s[42:43], v[196:197] op_sel_hi:[1,0,0]
	s_nop 0
	v_mul_f32_e32 v116, 0x4b800000, v115
	v_cmp_gt_f32_e32 vcc, s28, v115
	v_cmp_gt_f32_e64 s[6:7], s28, v114
	s_nop 0
	v_cndmask_b32_e32 v115, v115, v116, vcc
	v_rsq_f32_e32 v115, v115
	s_nop 0
	v_mul_f32_e32 v116, 0x45800000, v115
	v_cndmask_b32_e32 v115, v115, v116, vcc
	v_mul_f32_e32 v116, s17, v115
	v_pk_mul_f32 v[112:113], v[112:113], v[116:117] op_sel_hi:[1,0]
	v_pk_mul_f32 v[110:111], v[110:111], v[116:117] op_sel_hi:[1,0]
	v_pk_mul_f32 v[108:109], v[108:109], v[116:117] op_sel_hi:[1,0]
	s_and_b64 vcc, exec, s[4:5]
	v_pk_mul_f32 v[118:119], v[106:107], v[116:117] op_sel_hi:[1,0]
	s_cbranch_vccnz .LBB0_533
	v_mul_f32_e32 v107, 0x3d372713, v118
	v_mul_f32_e32 v107, v118, v107
	v_fma_f32 v107, v118, v107, v118
	v_mul_f32_e32 v107, 0x3fcc422a, v107
	v_mul_f32_e32 v107, 0xbfb8aa3b, v107
	v_exp_f32_e32 v107, v107
	v_mov_b32_e32 v115, v111
	v_mov_b32_e32 v117, v119
	v_mul_f32_e32 v106, 0x3d372713, v110
	v_add_f32_e32 v107, 1.0, v107
	v_rcp_f32_e32 v120, v107
	v_mul_f32_e32 v107, 0x3d372713, v111
	v_mul_f32_e32 v107, v111, v107
	v_fmac_f32_e32 v115, v115, v107
	v_mul_f32_e32 v107, 0x3fcc422a, v115
	v_mul_f32_e32 v115, 0x3d372713, v119
	v_mul_f32_e32 v115, v119, v115
	v_fmac_f32_e32 v117, v117, v115
	v_mul_f32_e32 v115, 0x3fcc422a, v117
	v_mul_f32_e32 v115, 0xbfb8aa3b, v115
	v_exp_f32_e32 v115, v115
	v_mul_f32_e32 v106, v110, v106
	v_fma_f32 v106, v110, v106, v110
	v_mul_f32_e32 v106, 0x3fcc422a, v106
	v_add_f32_e32 v115, 1.0, v115
	v_rcp_f32_e32 v121, v115
	v_mul_f32_e32 v115, 0x3d372713, v112
	v_mul_f32_e32 v115, v112, v115
	v_fma_f32 v115, v112, v115, v112
	v_mul_f32_e32 v115, 0x3fcc422a, v115
	v_mul_f32_e32 v115, 0xbfb8aa3b, v115
	v_exp_f32_e32 v115, v115
	v_mul_f32_e32 v106, 0xbfb8aa3b, v106
	v_mul_f32_e32 v107, 0xbfb8aa3b, v107
	v_exp_f32_e32 v106, v106
	v_add_f32_e32 v115, 1.0, v115
	v_rcp_f32_e32 v122, v115
	v_mul_f32_e32 v115, 0x3d372713, v108
	v_exp_f32_e32 v107, v107
	v_mul_f32_e32 v115, v108, v115
	v_fma_f32 v115, v108, v115, v108
	v_mul_f32_e32 v115, 0x3fcc422a, v115
	v_mul_f32_e32 v115, 0xbfb8aa3b, v115
	v_add_f32_e32 v106, 1.0, v106
	v_add_f32_e32 v107, 1.0, v107
	v_exp_f32_e32 v115, v115
	v_rcp_f32_e32 v106, v106
	v_rcp_f32_e32 v107, v107
	v_pk_mul_f32 v[118:119], v[118:119], v[120:121]
	v_add_f32_e32 v115, 1.0, v115
	v_rcp_f32_e32 v124, v115
	v_mul_f32_e32 v115, 0x3d372713, v113
	v_pk_mul_f32 v[110:111], v[110:111], v[106:107]
	v_mul_f32_e32 v106, 0x3d372713, v109
	v_mul_f32_e32 v115, v113, v115
	v_mul_f32_e32 v106, v109, v106
	v_fma_f32 v115, v113, v115, v113
	v_fma_f32 v106, v109, v106, v109
	v_mul_f32_e32 v115, 0x3fcc422a, v115
	v_mul_f32_e32 v106, 0x3fcc422a, v106
	v_mul_f32_e32 v115, 0xbfb8aa3b, v115
	v_mul_f32_e32 v106, 0xbfb8aa3b, v106
	v_exp_f32_e32 v115, v115
	v_exp_f32_e32 v106, v106
	v_add_f32_e32 v115, 1.0, v115
	v_add_f32_e32 v106, 1.0, v106
	v_rcp_f32_e32 v123, v115
	v_rcp_f32_e32 v125, v106
	v_pk_mul_f32 v[112:113], v[112:113], v[122:123]
	v_pk_mul_f32 v[108:109], v[108:109], v[124:125]
; __device__ __forceinline__ float fgelu_tanh(float v) { return v * fsig(1.5957691216057308f * (v + 0.044715f * v * v * v)); }
; __device__ __forceinline__ u32x4 pack8(const f32x4 v0, const f32x4 v1) { u32x4 w; w.x = cvt_pk_bf16(v0[0], v0[1]); w.y = cvt_pk_bf16(v0[2], v0[3]); w.z = cvt_pk_bf16(v1[0], v1[1]); w.w = cvt_pk_bf16(v1[2], v1[3]); return w; }
; __device__ __forceinline__ void rstd8(const float* ss, int row0, float sc, float (&rs)[2][4]) {
;     ...
;         for (int m = 0; m < 4; ++m) pa[ai][m] = *(const f32x4*)(ss + (size_t)(row0 + ai * HALF + m * 16) * 4);
; #pragma unroll
;     for (int ai = 0; ai < 2; ++ai)
; #pragma unroll
;         for (int m = 0; m < 4; ++m) { const f32x4 a = pa[ai][m]; rs[ai][m] = rsqrtf(((a[0] + a[1]) + (a[2] + a[3])) * (1.0f / 1024.0f) + 1e-6f) * sc; }
;     __device__ __forceinline__ void operator()(const f32x4 (&acc)[2][2][4][2], const Unit& u, int wr, int wc, int fr, int fq) const {
;     ...
;             for (int m = 0; m < 4; ++m) { const int row = row0 + ai * HALF + m * 16; const float rs = rsv[ai][m];
; #pragma unroll
;                 for (int bj = 0; bj < 2; ++bj) { f32x4 v0 = acc[ai][bj][m][0] * rs, v1 = acc[ai][bj][m][1] * rs;
;                     if (act) {
; #pragma unroll
;                         for (int i = 0; i < 4; ++i) { v0[i] = fgelu_tanh(v0[i]); v1[i] = fgelu_tanh(v1[i]); } }
;                     *(u32x4*)(dst + (size_t)row * ld + col0 + bj * HALF) = pack8(v0, v1); __builtin_amdgcn_sched_barrier(0); } }
.LBB0_533:
	v_mul_lo_u32 v115, s45, v176
	v_mul_lo_u32 v120, s44, v177
	v_mad_u64_u32 v[106:107], s[8:9], s44, v176, 0
	v_add3_u32 v107, v107, v120, v115
	v_lshl_add_u64 v[106:107], v[106:107], 1, v[146:147]
	v_mov_b32_e32 v117, v116
	v_cvt_pk_bf16_f32 v110, v110, v111
	v_cvt_pk_bf16_f32 v111, v112, v113
	v_cvt_pk_bf16_f32 v112, v118, v119
	v_cvt_pk_bf16_f32 v113, v108, v109
	global_store_dwordx4 v[106:107], v[110:113], off sc1
	v_mov_b32_e32 v108, v116
	v_mov_b32_e32 v109, v116
	v_pk_mul_f32 v[96:97], v[96:97], v[108:109]
	v_pk_mul_f32 v[94:95], v[94:95], v[116:117]
	v_pk_mul_f32 v[92:93], v[92:93], v[108:109]
	s_and_b64 vcc, exec, s[4:5]
	v_pk_mul_f32 v[90:91], v[90:91], v[116:117]
	s_cbranch_vccnz .LBB0_535
	v_mul_f32_e32 v109, 0x3d372713, v90
	v_mul_f32_e32 v109, v90, v109
	v_fma_f32 v109, v90, v109, v90
	v_mul_f32_e32 v109, 0x3fcc422a, v109
	v_mul_f32_e32 v109, 0xbfb8aa3b, v109
	v_exp_f32_e32 v109, v109
	v_mul_f32_e32 v108, 0x3d372713, v94
	v_mul_f32_e32 v108, v94, v108
	v_mov_b32_e32 v111, v95
	v_add_f32_e32 v109, 1.0, v109
	v_rcp_f32_e32 v110, v109
	v_mul_f32_e32 v109, 0x3d372713, v95
	v_mul_f32_e32 v109, v95, v109
	v_fma_f32 v108, v94, v108, v94
	v_fmac_f32_e32 v111, v111, v109
	v_mul_f32_e32 v108, 0x3fcc422a, v108
	v_mul_f32_e32 v109, 0x3fcc422a, v111
	v_mul_f32_e32 v108, 0xbfb8aa3b, v108
	v_mul_f32_e32 v109, 0xbfb8aa3b, v109
	v_mul_f32_e32 v113, 0x3d372713, v92
	v_exp_f32_e32 v108, v108
	v_exp_f32_e32 v109, v109
	v_mul_f32_e32 v113, v92, v113
	v_fma_f32 v113, v92, v113, v92
	v_mul_f32_e32 v113, 0x3fcc422a, v113
	v_mul_f32_e32 v113, 0xbfb8aa3b, v113
	v_add_f32_e32 v108, 1.0, v108
	v_add_f32_e32 v109, 1.0, v109
	v_exp_f32_e32 v113, v113
	v_rcp_f32_e32 v108, v108
	v_rcp_f32_e32 v109, v109
	v_mul_f32_e32 v111, 0x3d372713, v91
	v_mul_f32_e32 v111, v91, v111
	v_mov_b32_e32 v112, v91
	v_fmac_f32_e32 v112, v112, v111
	v_add_f32_e32 v113, 1.0, v113
	v_mul_f32_e32 v111, 0x3fcc422a, v112
	v_mul_f32_e32 v112, 0x3d372713, v96
	v_rcp_f32_e32 v116, v113
	v_mul_f32_e32 v113, 0x3d372713, v97
	v_pk_mul_f32 v[94:95], v[94:95], v[108:109]
	v_mul_f32_e32 v108, 0x3d372713, v93
	v_mul_f32_e32 v112, v96, v112
	v_mul_f32_e32 v113, v97, v113
	v_mul_f32_e32 v108, v93, v108
	v_fma_f32 v112, v96, v112, v96
	v_fma_f32 v113, v97, v113, v97
	v_fma_f32 v108, v93, v108, v93
	v_mul_f32_e32 v112, 0x3fcc422a, v112
	v_mul_f32_e32 v113, 0x3fcc422a, v113
	v_mul_f32_e32 v108, 0x3fcc422a, v108
	v_mul_f32_e32 v111, 0xbfb8aa3b, v111
	v_mul_f32_e32 v112, 0xbfb8aa3b, v112
	v_mul_f32_e32 v113, 0xbfb8aa3b, v113
	v_mul_f32_e32 v108, 0xbfb8aa3b, v108
	v_exp_f32_e32 v111, v111
	v_exp_f32_e32 v112, v112
	v_exp_f32_e32 v113, v113
	v_exp_f32_e32 v108, v108
	v_add_f32_e32 v111, 1.0, v111
	v_add_f32_e32 v112, 1.0, v112
	v_add_f32_e32 v113, 1.0, v113
	v_add_f32_e32 v108, 1.0, v108
	v_rcp_f32_e32 v111, v111
	v_rcp_f32_e32 v112, v112
	v_rcp_f32_e32 v113, v113
	v_rcp_f32_e32 v117, v108
	v_pk_mul_f32 v[90:91], v[90:91], v[110:111]
	v_pk_mul_f32 v[96:97], v[96:97], v[112:113]
	v_pk_mul_f32 v[92:93], v[92:93], v[116:117]
.LBB0_535:
	v_mul_f32_e32 v108, 0x4b800000, v114
	v_cndmask_b32_e64 v108, v114, v108, s[6:7]
	v_rsq_f32_e32 v108, v108
	v_cvt_pk_bf16_f32 v94, v94, v95
	v_cvt_pk_bf16_f32 v95, v96, v97
	v_cvt_pk_bf16_f32 v96, v90, v91
	v_cvt_pk_bf16_f32 v97, v92, v93
	global_store_dwordx4 v[106:107], v[94:97], off offset:256 sc1
	v_mul_f32_e32 v90, 0x45800000, v108
	v_cndmask_b32_e64 v90, v108, v90, s[6:7]
	v_mul_f32_e32 v90, s17, v90
	v_pk_mul_f32 v[88:89], v[88:89], v[90:91] op_sel_hi:[1,0]
	v_pk_mul_f32 v[86:87], v[86:87], v[90:91] op_sel_hi:[1,0]
	v_pk_mul_f32 v[84:85], v[84:85], v[90:91] op_sel_hi:[1,0]
	s_and_b64 vcc, exec, s[4:5]
	v_pk_mul_f32 v[92:93], v[82:83], v[90:91] op_sel_hi:[1,0]
	s_cbranch_vccnz .LBB0_537
	v_mul_f32_e32 v83, 0x3d372713, v92
	v_mul_f32_e32 v83, v92, v83
	v_fma_f32 v83, v92, v83, v92
	v_mul_f32_e32 v83, 0x3fcc422a, v83
	v_mul_f32_e32 v83, 0xbfb8aa3b, v83
	v_exp_f32_e32 v83, v83
	v_mov_b32_e32 v91, v87
	v_mov_b32_e32 v95, v93
	v_mul_f32_e32 v82, 0x3d372713, v86
	v_add_f32_e32 v83, 1.0, v83
	v_rcp_f32_e32 v94, v83
	v_mul_f32_e32 v83, 0x3d372713, v87
	v_mul_f32_e32 v83, v87, v83
	v_fmac_f32_e32 v91, v91, v83
	v_mul_f32_e32 v83, 0x3fcc422a, v91
	v_mul_f32_e32 v91, 0x3d372713, v93
	v_mul_f32_e32 v91, v93, v91
	v_fmac_f32_e32 v95, v95, v91
	v_mul_f32_e32 v91, 0x3fcc422a, v95
	v_mul_f32_e32 v91, 0xbfb8aa3b, v91
	v_exp_f32_e32 v91, v91
	v_mul_f32_e32 v82, v86, v82
	v_fma_f32 v82, v86, v82, v86
	v_mul_f32_e32 v82, 0x3fcc422a, v82
	v_add_f32_e32 v91, 1.0, v91
	v_rcp_f32_e32 v95, v91
	v_mul_f32_e32 v91, 0x3d372713, v88
	v_mul_f32_e32 v91, v88, v91
	v_fma_f32 v91, v88, v91, v88
	v_mul_f32_e32 v91, 0x3fcc422a, v91
	v_mul_f32_e32 v91, 0xbfb8aa3b, v91
	v_exp_f32_e32 v91, v91
	v_mul_f32_e32 v82, 0xbfb8aa3b, v82
	v_mul_f32_e32 v83, 0xbfb8aa3b, v83
	v_exp_f32_e32 v82, v82
	v_add_f32_e32 v91, 1.0, v91
	v_rcp_f32_e32 v96, v91
	v_mul_f32_e32 v91, 0x3d372713, v84
	v_exp_f32_e32 v83, v83
	v_mul_f32_e32 v91, v84, v91
	v_fma_f32 v91, v84, v91, v84
	v_mul_f32_e32 v91, 0x3fcc422a, v91
	v_mul_f32_e32 v91, 0xbfb8aa3b, v91
	v_add_f32_e32 v82, 1.0, v82
	v_add_f32_e32 v83, 1.0, v83
	v_exp_f32_e32 v91, v91
	v_rcp_f32_e32 v82, v82
	v_rcp_f32_e32 v83, v83
	v_pk_mul_f32 v[92:93], v[92:93], v[94:95]
	v_add_f32_e32 v91, 1.0, v91
	v_rcp_f32_e32 v106, v91
	v_mul_f32_e32 v91, 0x3d372713, v89
	v_pk_mul_f32 v[86:87], v[86:87], v[82:83]
	v_mul_f32_e32 v82, 0x3d372713, v85
	v_mul_f32_e32 v91, v89, v91
	v_mul_f32_e32 v82, v85, v82
	v_fma_f32 v91, v89, v91, v89
	v_fma_f32 v82, v85, v82, v85
	v_mul_f32_e32 v91, 0x3fcc422a, v91
	v_mul_f32_e32 v82, 0x3fcc422a, v82
	v_mul_f32_e32 v91, 0xbfb8aa3b, v91
	v_mul_f32_e32 v82, 0xbfb8aa3b, v82
	v_exp_f32_e32 v91, v91
	v_exp_f32_e32 v82, v82
	v_add_f32_e32 v91, 1.0, v91
	v_add_f32_e32 v82, 1.0, v82
	v_rcp_f32_e32 v97, v91
	v_rcp_f32_e32 v107, v82
	v_pk_mul_f32 v[88:89], v[88:89], v[96:97]
	v_pk_mul_f32 v[84:85], v[84:85], v[106:107]
; __device__ __forceinline__ float fgelu_tanh(float v) { return v * fsig(1.5957691216057308f * (v + 0.044715f * v * v * v)); }
; __device__ __forceinline__ u32x4 pack8(const f32x4 v0, const f32x4 v1) { u32x4 w; w.x = cvt_pk_bf16(v0[0], v0[1]); w.y = cvt_pk_bf16(v0[2], v0[3]); w.z = cvt_pk_bf16(v1[0], v1[1]); w.w = cvt_pk_bf16(v1[2], v1[3]); return w; }
; __device__ __forceinline__ void rstd8(const float* ss, int row0, float sc, float (&rs)[2][4]) {
;     ...
;         for (int m = 0; m < 4; ++m) pa[ai][m] = *(const f32x4*)(ss + (size_t)(row0 + ai * HALF + m * 16) * 4);
; #pragma unroll
;     for (int ai = 0; ai < 2; ++ai)
; #pragma unroll
;         for (int m = 0; m < 4; ++m) { const f32x4 a = pa[ai][m]; rs[ai][m] = rsqrtf(((a[0] + a[1]) + (a[2] + a[3])) * (1.0f / 1024.0f) + 1e-6f) * sc; }
;     __device__ __forceinline__ void operator()(const f32x4 (&acc)[2][2][4][2], const Unit& u, int wr, int wc, int fr, int fq) const {
;     ...
;             for (int m = 0; m < 4; ++m) { const int row = row0 + ai * HALF + m * 16; const float rs = rsv[ai][m];
; #pragma unroll
;                 for (int bj = 0; bj < 2; ++bj) { f32x4 v0 = acc[ai][bj][m][0] * rs, v1 = acc[ai][bj][m][1] * rs;
;                     if (act) {
; #pragma unroll
;                         for (int i = 0; i < 4; ++i) { v0[i] = fgelu_tanh(v0[i]); v1[i] = fgelu_tanh(v1[i]); } }
;                     *(u32x4*)(dst + (size_t)row * ld + col0 + bj * HALF) = pack8(v0, v1); __builtin_amdgcn_sched_barrier(0); } }
.LBB0_537:
	v_mul_lo_u32 v94, s45, v174
	v_mul_lo_u32 v95, s44, v175
	v_mad_u64_u32 v[82:83], s[6:7], s44, v174, 0
	v_add3_u32 v83, v83, v95, v94
	v_lshl_add_u64 v[82:83], v[82:83], 1, v[146:147]
	v_mov_b32_e32 v91, v90
	v_cvt_pk_bf16_f32 v86, v86, v87
	v_cvt_pk_bf16_f32 v87, v88, v89
	v_cvt_pk_bf16_f32 v88, v92, v93
	v_cvt_pk_bf16_f32 v89, v84, v85
	global_store_dwordx4 v[82:83], v[86:89], off sc1
	s_nop 1
	v_mov_b32_e32 v86, v90
	v_mov_b32_e32 v87, v90
	v_pk_mul_f32 v[80:81], v[80:81], v[86:87]
	v_pk_mul_f32 v[84:85], v[78:79], v[90:91]
	v_pk_mul_f32 v[78:79], v[76:77], v[86:87]
	s_and_b64 vcc, exec, s[4:5]
	v_pk_mul_f32 v[86:87], v[74:75], v[90:91]
	s_cbranch_vccnz .LBB0_539
	v_mul_f32_e32 v75, 0x3d372713, v86
	v_mul_f32_e32 v75, v86, v75
	v_fma_f32 v75, v86, v75, v86
	v_mul_f32_e32 v75, 0x3fcc422a, v75
	v_mul_f32_e32 v75, 0xbfb8aa3b, v75
	v_exp_f32_e32 v75, v75
	v_mul_f32_e32 v74, 0x3d372713, v84
	v_mul_f32_e32 v74, v84, v74
	v_mov_b32_e32 v77, v85
	v_add_f32_e32 v75, 1.0, v75
	v_rcp_f32_e32 v76, v75
	v_mul_f32_e32 v75, 0x3d372713, v85
	v_mul_f32_e32 v75, v85, v75
	v_fma_f32 v74, v84, v74, v84
	v_fmac_f32_e32 v77, v77, v75
	v_mul_f32_e32 v74, 0x3fcc422a, v74
	v_mul_f32_e32 v75, 0x3fcc422a, v77
	v_mul_f32_e32 v74, 0xbfb8aa3b, v74
	v_mul_f32_e32 v75, 0xbfb8aa3b, v75
	v_mul_f32_e32 v89, 0x3d372713, v78
	v_exp_f32_e32 v74, v74
	v_exp_f32_e32 v75, v75
	v_mul_f32_e32 v89, v78, v89
	v_fma_f32 v89, v78, v89, v78
	v_mul_f32_e32 v89, 0x3fcc422a, v89
	v_mul_f32_e32 v89, 0xbfb8aa3b, v89
	v_add_f32_e32 v74, 1.0, v74
	v_add_f32_e32 v75, 1.0, v75
	v_exp_f32_e32 v89, v89
	v_rcp_f32_e32 v74, v74
	v_rcp_f32_e32 v75, v75
	v_mul_f32_e32 v77, 0x3d372713, v87
	v_mul_f32_e32 v77, v87, v77
	v_mov_b32_e32 v88, v87
	v_fmac_f32_e32 v88, v88, v77
	v_add_f32_e32 v89, 1.0, v89
	v_mul_f32_e32 v77, 0x3fcc422a, v88
	v_mul_f32_e32 v88, 0x3d372713, v80
	v_rcp_f32_e32 v90, v89
	v_mul_f32_e32 v89, 0x3d372713, v81
	v_pk_mul_f32 v[84:85], v[84:85], v[74:75]
	v_mul_f32_e32 v74, 0x3d372713, v79
	v_mul_f32_e32 v88, v80, v88
	v_mul_f32_e32 v89, v81, v89
	v_mul_f32_e32 v74, v79, v74
	v_fma_f32 v88, v80, v88, v80
	v_fma_f32 v89, v81, v89, v81
	v_fma_f32 v74, v79, v74, v79
	v_mul_f32_e32 v88, 0x3fcc422a, v88
	v_mul_f32_e32 v89, 0x3fcc422a, v89
	v_mul_f32_e32 v74, 0x3fcc422a, v74
	v_mul_f32_e32 v77, 0xbfb8aa3b, v77
	v_mul_f32_e32 v88, 0xbfb8aa3b, v88
	v_mul_f32_e32 v89, 0xbfb8aa3b, v89
	v_mul_f32_e32 v74, 0xbfb8aa3b, v74
	v_exp_f32_e32 v77, v77
	v_exp_f32_e32 v88, v88
	v_exp_f32_e32 v89, v89
	v_exp_f32_e32 v74, v74
	v_add_f32_e32 v77, 1.0, v77
	v_add_f32_e32 v88, 1.0, v88
	v_add_f32_e32 v89, 1.0, v89
	v_add_f32_e32 v74, 1.0, v74
	v_rcp_f32_e32 v77, v77
	v_rcp_f32_e32 v88, v88
	v_rcp_f32_e32 v89, v89
	v_rcp_f32_e32 v91, v74
	v_pk_mul_f32 v[86:87], v[86:87], v[76:77]
	v_pk_mul_f32 v[80:81], v[80:81], v[88:89]
	v_pk_mul_f32 v[78:79], v[78:79], v[90:91]
.LBB0_539:
	v_mov_b32_e32 v74, v103
	v_mov_b32_e32 v75, v104
	v_mov_b32_e32 v103, v105
	v_mov_b32_e32 v76, v99
	v_mov_b32_e32 v77, v100
	v_mov_b32_e32 v99, v101
	v_pk_add_f32 v[74:75], v[74:75], v[102:103]
	v_pk_add_f32 v[76:77], v[76:77], v[98:99]
	v_mov_b32_e32 v89, v74
	v_mov_b32_e32 v88, v76
	v_mov_b32_e32 v74, v77
	v_pk_add_f32 v[74:75], v[88:89], v[74:75]
	v_cvt_pk_bf16_f32 v84, v84, v85
	v_cvt_pk_bf16_f32 v85, v80, v81
	v_cvt_pk_bf16_f32 v86, v86, v87
	v_cvt_pk_bf16_f32 v87, v78, v79
	global_store_dwordx4 v[82:83], v[84:87], off offset:256 sc1
	v_pk_fma_f32 v[74:75], v[74:75], s[42:43], v[196:197] op_sel_hi:[1,0,0]
	s_nop 0
	v_mul_f32_e32 v76, 0x4b800000, v75
	v_cmp_gt_f32_e32 vcc, s28, v75
	v_cmp_gt_f32_e64 s[6:7], s28, v74
	s_nop 0
	v_cndmask_b32_e32 v75, v75, v76, vcc
	v_rsq_f32_e32 v75, v75
	s_nop 0
	v_mul_f32_e32 v76, 0x45800000, v75
	v_cndmask_b32_e32 v75, v75, v76, vcc
	v_mul_f32_e32 v76, s17, v75
	v_pk_mul_f32 v[62:63], v[62:63], v[76:77] op_sel_hi:[1,0]
	v_pk_mul_f32 v[60:61], v[60:61], v[76:77] op_sel_hi:[1,0]
	v_pk_mul_f32 v[58:59], v[58:59], v[76:77] op_sel_hi:[1,0]
	s_and_b64 vcc, exec, s[4:5]
	v_pk_mul_f32 v[78:79], v[56:57], v[76:77] op_sel_hi:[1,0]
	s_cbranch_vccnz .LBB0_541
	v_mul_f32_e32 v57, 0x3d372713, v78
	v_mul_f32_e32 v57, v78, v57
	v_fma_f32 v57, v78, v57, v78
	v_mul_f32_e32 v57, 0x3fcc422a, v57
	v_mul_f32_e32 v57, 0xbfb8aa3b, v57
	v_exp_f32_e32 v57, v57
	v_mov_b32_e32 v75, v61
	v_mov_b32_e32 v77, v79
	v_mul_f32_e32 v56, 0x3d372713, v60
	v_add_f32_e32 v57, 1.0, v57
	v_rcp_f32_e32 v80, v57
	v_mul_f32_e32 v57, 0x3d372713, v61
	v_mul_f32_e32 v57, v61, v57
	v_fmac_f32_e32 v75, v75, v57
	v_mul_f32_e32 v57, 0x3fcc422a, v75
	v_mul_f32_e32 v75, 0x3d372713, v79
	v_mul_f32_e32 v75, v79, v75
	v_fmac_f32_e32 v77, v77, v75
	v_mul_f32_e32 v75, 0x3fcc422a, v77
	v_mul_f32_e32 v75, 0xbfb8aa3b, v75
	v_exp_f32_e32 v75, v75
	v_mul_f32_e32 v56, v60, v56
	v_fma_f32 v56, v60, v56, v60
	v_mul_f32_e32 v56, 0x3fcc422a, v56
	v_add_f32_e32 v75, 1.0, v75
	v_rcp_f32_e32 v81, v75
	v_mul_f32_e32 v75, 0x3d372713, v62
	v_mul_f32_e32 v75, v62, v75
	v_fma_f32 v75, v62, v75, v62
	v_mul_f32_e32 v75, 0x3fcc422a, v75
	v_mul_f32_e32 v75, 0xbfb8aa3b, v75
	v_exp_f32_e32 v75, v75
	v_mul_f32_e32 v56, 0xbfb8aa3b, v56
	v_mul_f32_e32 v57, 0xbfb8aa3b, v57
	v_exp_f32_e32 v56, v56
	v_add_f32_e32 v75, 1.0, v75
	v_rcp_f32_e32 v82, v75
	v_mul_f32_e32 v75, 0x3d372713, v58
	v_exp_f32_e32 v57, v57
	v_mul_f32_e32 v75, v58, v75
	v_fma_f32 v75, v58, v75, v58
	v_mul_f32_e32 v75, 0x3fcc422a, v75
	v_mul_f32_e32 v75, 0xbfb8aa3b, v75
	v_add_f32_e32 v56, 1.0, v56
	v_add_f32_e32 v57, 1.0, v57
	v_exp_f32_e32 v75, v75
	v_rcp_f32_e32 v56, v56
	v_rcp_f32_e32 v57, v57
	v_pk_mul_f32 v[78:79], v[78:79], v[80:81]
	v_add_f32_e32 v75, 1.0, v75
	v_rcp_f32_e32 v84, v75
	v_mul_f32_e32 v75, 0x3d372713, v63
	v_pk_mul_f32 v[60:61], v[60:61], v[56:57]
	v_mul_f32_e32 v56, 0x3d372713, v59
	v_mul_f32_e32 v75, v63, v75
	v_mul_f32_e32 v56, v59, v56
	v_fma_f32 v75, v63, v75, v63
	v_fma_f32 v56, v59, v56, v59
	v_mul_f32_e32 v75, 0x3fcc422a, v75
	v_mul_f32_e32 v56, 0x3fcc422a, v56
	v_mul_f32_e32 v75, 0xbfb8aa3b, v75
	v_mul_f32_e32 v56, 0xbfb8aa3b, v56
	v_exp_f32_e32 v75, v75
	v_exp_f32_e32 v56, v56
	v_add_f32_e32 v75, 1.0, v75
	v_add_f32_e32 v56, 1.0, v56
	v_rcp_f32_e32 v83, v75
	v_rcp_f32_e32 v85, v56
	v_pk_mul_f32 v[62:63], v[62:63], v[82:83]
	v_pk_mul_f32 v[58:59], v[58:59], v[84:85]
; __device__ __forceinline__ float fgelu_tanh(float v) { return v * fsig(1.5957691216057308f * (v + 0.044715f * v * v * v)); }
; __device__ __forceinline__ u32x4 pack8(const f32x4 v0, const f32x4 v1) { u32x4 w; w.x = cvt_pk_bf16(v0[0], v0[1]); w.y = cvt_pk_bf16(v0[2], v0[3]); w.z = cvt_pk_bf16(v1[0], v1[1]); w.w = cvt_pk_bf16(v1[2], v1[3]); return w; }
; __device__ __forceinline__ void rstd8(const float* ss, int row0, float sc, float (&rs)[2][4]) {
;     ...
;         for (int m = 0; m < 4; ++m) pa[ai][m] = *(const f32x4*)(ss + (size_t)(row0 + ai * HALF + m * 16) * 4);
; #pragma unroll
;     for (int ai = 0; ai < 2; ++ai)
; #pragma unroll
;         for (int m = 0; m < 4; ++m) { const f32x4 a = pa[ai][m]; rs[ai][m] = rsqrtf(((a[0] + a[1]) + (a[2] + a[3])) * (1.0f / 1024.0f) + 1e-6f) * sc; }
;     __device__ __forceinline__ void operator()(const f32x4 (&acc)[2][2][4][2], const Unit& u, int wr, int wc, int fr, int fq) const {
;     ...
;             for (int m = 0; m < 4; ++m) { const int row = row0 + ai * HALF + m * 16; const float rs = rsv[ai][m];
; #pragma unroll
;                 for (int bj = 0; bj < 2; ++bj) { f32x4 v0 = acc[ai][bj][m][0] * rs, v1 = acc[ai][bj][m][1] * rs;
;                     if (act) {
; #pragma unroll
;                         for (int i = 0; i < 4; ++i) { v0[i] = fgelu_tanh(v0[i]); v1[i] = fgelu_tanh(v1[i]); } }
;                     *(u32x4*)(dst + (size_t)row * ld + col0 + bj * HALF) = pack8(v0, v1); __builtin_amdgcn_sched_barrier(0); } }
.LBB0_541:
	v_mul_lo_u32 v75, s45, v172
	v_mul_lo_u32 v80, s44, v173
	v_mad_u64_u32 v[56:57], s[8:9], s44, v172, 0
	v_add3_u32 v57, v57, v80, v75
	v_lshl_add_u64 v[56:57], v[56:57], 1, v[146:147]
	v_mov_b32_e32 v77, v76
	v_cvt_pk_bf16_f32 v60, v60, v61
	v_cvt_pk_bf16_f32 v61, v62, v63
	v_cvt_pk_bf16_f32 v62, v78, v79
	v_cvt_pk_bf16_f32 v63, v58, v59
	global_store_dwordx4 v[56:57], v[60:63], off sc1
	v_mov_b32_e32 v58, v76
	v_mov_b32_e32 v59, v76
	v_pk_mul_f32 v[54:55], v[54:55], v[58:59]
	v_pk_mul_f32 v[52:53], v[52:53], v[76:77]
	v_pk_mul_f32 v[50:51], v[50:51], v[58:59]
	s_and_b64 vcc, exec, s[4:5]
	v_pk_mul_f32 v[48:49], v[48:49], v[76:77]
	s_cbranch_vccnz .LBB0_543
	v_mul_f32_e32 v59, 0x3d372713, v48
	v_mul_f32_e32 v59, v48, v59
	v_fma_f32 v59, v48, v59, v48
	v_mul_f32_e32 v59, 0x3fcc422a, v59
	v_mul_f32_e32 v59, 0xbfb8aa3b, v59
	v_exp_f32_e32 v59, v59
	v_mul_f32_e32 v58, 0x3d372713, v52
	v_mul_f32_e32 v58, v52, v58
	v_mov_b32_e32 v61, v53
	v_add_f32_e32 v59, 1.0, v59
	v_rcp_f32_e32 v60, v59
	v_mul_f32_e32 v59, 0x3d372713, v53
	v_mul_f32_e32 v59, v53, v59
	v_fma_f32 v58, v52, v58, v52
	v_fmac_f32_e32 v61, v61, v59
	v_mul_f32_e32 v58, 0x3fcc422a, v58
	v_mul_f32_e32 v59, 0x3fcc422a, v61
	v_mul_f32_e32 v58, 0xbfb8aa3b, v58
	v_mul_f32_e32 v59, 0xbfb8aa3b, v59
	v_mul_f32_e32 v63, 0x3d372713, v50
	v_exp_f32_e32 v58, v58
	v_exp_f32_e32 v59, v59
	v_mul_f32_e32 v63, v50, v63
	v_fma_f32 v63, v50, v63, v50
	v_mul_f32_e32 v63, 0x3fcc422a, v63
	v_mul_f32_e32 v63, 0xbfb8aa3b, v63
	v_add_f32_e32 v58, 1.0, v58
	v_add_f32_e32 v59, 1.0, v59
	v_exp_f32_e32 v63, v63
	v_rcp_f32_e32 v58, v58
	v_rcp_f32_e32 v59, v59
	v_mul_f32_e32 v61, 0x3d372713, v49
	v_mul_f32_e32 v61, v49, v61
	v_mov_b32_e32 v62, v49
	v_fmac_f32_e32 v62, v62, v61
	v_add_f32_e32 v63, 1.0, v63
	v_mul_f32_e32 v61, 0x3fcc422a, v62
	v_mul_f32_e32 v62, 0x3d372713, v54
	v_rcp_f32_e32 v76, v63
	v_mul_f32_e32 v63, 0x3d372713, v55
	v_pk_mul_f32 v[52:53], v[52:53], v[58:59]
	v_mul_f32_e32 v58, 0x3d372713, v51
	v_mul_f32_e32 v62, v54, v62
	v_mul_f32_e32 v63, v55, v63
	v_mul_f32_e32 v58, v51, v58
	v_fma_f32 v62, v54, v62, v54
	v_fma_f32 v63, v55, v63, v55
	v_fma_f32 v58, v51, v58, v51
	v_mul_f32_e32 v62, 0x3fcc422a, v62
	v_mul_f32_e32 v63, 0x3fcc422a, v63
	v_mul_f32_e32 v58, 0x3fcc422a, v58
	v_mul_f32_e32 v61, 0xbfb8aa3b, v61
	v_mul_f32_e32 v62, 0xbfb8aa3b, v62
	v_mul_f32_e32 v63, 0xbfb8aa3b, v63
	v_mul_f32_e32 v58, 0xbfb8aa3b, v58
	v_exp_f32_e32 v61, v61
	v_exp_f32_e32 v62, v62
	v_exp_f32_e32 v63, v63
	v_exp_f32_e32 v58, v58
	v_add_f32_e32 v61, 1.0, v61
	v_add_f32_e32 v62, 1.0, v62
	v_add_f32_e32 v63, 1.0, v63
	v_add_f32_e32 v58, 1.0, v58
	v_rcp_f32_e32 v61, v61
	v_rcp_f32_e32 v62, v62
	v_rcp_f32_e32 v63, v63
	v_rcp_f32_e32 v77, v58
	v_pk_mul_f32 v[48:49], v[48:49], v[60:61]
	v_pk_mul_f32 v[54:55], v[54:55], v[62:63]
	v_pk_mul_f32 v[50:51], v[50:51], v[76:77]
.LBB0_543:
	v_mul_f32_e32 v58, 0x4b800000, v74
	v_cndmask_b32_e64 v58, v74, v58, s[6:7]
	v_rsq_f32_e32 v58, v58
	v_cvt_pk_bf16_f32 v52, v52, v53
	v_cvt_pk_bf16_f32 v53, v54, v55
	v_cvt_pk_bf16_f32 v54, v48, v49
	v_cvt_pk_bf16_f32 v55, v50, v51
	global_store_dwordx4 v[56:57], v[52:55], off offset:256 sc1
	v_mul_f32_e32 v48, 0x45800000, v58
	v_cndmask_b32_e64 v48, v58, v48, s[6:7]
	v_mul_f32_e32 v48, s17, v48
	v_pk_mul_f32 v[46:47], v[46:47], v[48:49] op_sel_hi:[1,0]
	v_pk_mul_f32 v[44:45], v[44:45], v[48:49] op_sel_hi:[1,0]
	v_pk_mul_f32 v[42:43], v[42:43], v[48:49] op_sel_hi:[1,0]
	s_and_b64 vcc, exec, s[4:5]
	v_pk_mul_f32 v[50:51], v[40:41], v[48:49] op_sel_hi:[1,0]
	s_cbranch_vccnz .LBB0_545
	v_mul_f32_e32 v41, 0x3d372713, v50
	v_mul_f32_e32 v41, v50, v41
	v_fma_f32 v41, v50, v41, v50
	v_mul_f32_e32 v41, 0x3fcc422a, v41
	v_mul_f32_e32 v41, 0xbfb8aa3b, v41
	v_exp_f32_e32 v41, v41
	v_mov_b32_e32 v49, v45
	v_mov_b32_e32 v53, v51
	v_mul_f32_e32 v40, 0x3d372713, v44
	v_add_f32_e32 v41, 1.0, v41
	v_rcp_f32_e32 v52, v41
	v_mul_f32_e32 v41, 0x3d372713, v45
	v_mul_f32_e32 v41, v45, v41
	v_fmac_f32_e32 v49, v49, v41
	v_mul_f32_e32 v41, 0x3fcc422a, v49
	v_mul_f32_e32 v49, 0x3d372713, v51
	v_mul_f32_e32 v49, v51, v49
	v_fmac_f32_e32 v53, v53, v49
	v_mul_f32_e32 v49, 0x3fcc422a, v53
	v_mul_f32_e32 v49, 0xbfb8aa3b, v49
	v_exp_f32_e32 v49, v49
	v_mul_f32_e32 v40, v44, v40
	v_fma_f32 v40, v44, v40, v44
	v_mul_f32_e32 v40, 0x3fcc422a, v40
	v_add_f32_e32 v49, 1.0, v49
	v_rcp_f32_e32 v53, v49
	v_mul_f32_e32 v49, 0x3d372713, v46
	v_mul_f32_e32 v49, v46, v49
	v_fma_f32 v49, v46, v49, v46
	v_mul_f32_e32 v49, 0x3fcc422a, v49
	v_mul_f32_e32 v49, 0xbfb8aa3b, v49
	v_exp_f32_e32 v49, v49
	v_mul_f32_e32 v40, 0xbfb8aa3b, v40
	v_mul_f32_e32 v41, 0xbfb8aa3b, v41
	v_exp_f32_e32 v40, v40
	v_add_f32_e32 v49, 1.0, v49
	v_rcp_f32_e32 v54, v49
	v_mul_f32_e32 v49, 0x3d372713, v42
	v_exp_f32_e32 v41, v41
	v_mul_f32_e32 v49, v42, v49
	v_fma_f32 v49, v42, v49, v42
	v_mul_f32_e32 v49, 0x3fcc422a, v49
	v_mul_f32_e32 v49, 0xbfb8aa3b, v49
	v_add_f32_e32 v40, 1.0, v40
	v_add_f32_e32 v41, 1.0, v41
	v_exp_f32_e32 v49, v49
	v_rcp_f32_e32 v40, v40
	v_rcp_f32_e32 v41, v41
	v_pk_mul_f32 v[50:51], v[50:51], v[52:53]
	v_add_f32_e32 v49, 1.0, v49
	v_rcp_f32_e32 v56, v49
	v_mul_f32_e32 v49, 0x3d372713, v47
	v_pk_mul_f32 v[44:45], v[44:45], v[40:41]
	v_mul_f32_e32 v40, 0x3d372713, v43
	v_mul_f32_e32 v49, v47, v49
	v_mul_f32_e32 v40, v43, v40
	v_fma_f32 v49, v47, v49, v47
	v_fma_f32 v40, v43, v40, v43
	v_mul_f32_e32 v49, 0x3fcc422a, v49
	v_mul_f32_e32 v40, 0x3fcc422a, v40
	v_mul_f32_e32 v49, 0xbfb8aa3b, v49
	v_mul_f32_e32 v40, 0xbfb8aa3b, v40
	v_exp_f32_e32 v49, v49
	v_exp_f32_e32 v40, v40
	v_add_f32_e32 v49, 1.0, v49
	v_add_f32_e32 v40, 1.0, v40
	v_rcp_f32_e32 v55, v49
	v_rcp_f32_e32 v57, v40
	v_pk_mul_f32 v[46:47], v[46:47], v[54:55]
	v_pk_mul_f32 v[42:43], v[42:43], v[56:57]
; __device__ __forceinline__ float fgelu_tanh(float v) { return v * fsig(1.5957691216057308f * (v + 0.044715f * v * v * v)); }
; __device__ __forceinline__ u32x4 pack8(const f32x4 v0, const f32x4 v1) { u32x4 w; w.x = cvt_pk_bf16(v0[0], v0[1]); w.y = cvt_pk_bf16(v0[2], v0[3]); w.z = cvt_pk_bf16(v1[0], v1[1]); w.w = cvt_pk_bf16(v1[2], v1[3]); return w; }
; __device__ __forceinline__ void rstd8(const float* ss, int row0, float sc, float (&rs)[2][4]) {
;     ...
;         for (int m = 0; m < 4; ++m) pa[ai][m] = *(const f32x4*)(ss + (size_t)(row0 + ai * HALF + m * 16) * 4);
; #pragma unroll
;     for (int ai = 0; ai < 2; ++ai)
; #pragma unroll
;         for (int m = 0; m < 4; ++m) { const f32x4 a = pa[ai][m]; rs[ai][m] = rsqrtf(((a[0] + a[1]) + (a[2] + a[3])) * (1.0f / 1024.0f) + 1e-6f) * sc; }
;     __device__ __forceinline__ void operator()(const f32x4 (&acc)[2][2][4][2], const Unit& u, int wr, int wc, int fr, int fq) const {
;     ...
;             for (int m = 0; m < 4; ++m) { const int row = row0 + ai * HALF + m * 16; const float rs = rsv[ai][m];
; #pragma unroll
;                 for (int bj = 0; bj < 2; ++bj) { f32x4 v0 = acc[ai][bj][m][0] * rs, v1 = acc[ai][bj][m][1] * rs;
;                     if (act) {
; #pragma unroll
;                         for (int i = 0; i < 4; ++i) { v0[i] = fgelu_tanh(v0[i]); v1[i] = fgelu_tanh(v1[i]); } }
;                     *(u32x4*)(dst + (size_t)row * ld + col0 + bj * HALF) = pack8(v0, v1); __builtin_amdgcn_sched_barrier(0); } }
.LBB0_545:
	v_mul_lo_u32 v52, s45, v170
	v_mul_lo_u32 v53, s44, v171
	v_mad_u64_u32 v[40:41], s[6:7], s44, v170, 0
	v_add3_u32 v41, v41, v53, v52
	v_lshl_add_u64 v[40:41], v[40:41], 1, v[146:147]
	v_mov_b32_e32 v49, v48
	v_cvt_pk_bf16_f32 v44, v44, v45
	v_cvt_pk_bf16_f32 v45, v46, v47
	v_cvt_pk_bf16_f32 v46, v50, v51
	v_cvt_pk_bf16_f32 v47, v42, v43
	global_store_dwordx4 v[40:41], v[44:47], off sc1
	s_nop 1
	v_mov_b32_e32 v44, v48
	v_mov_b32_e32 v45, v48
	v_pk_mul_f32 v[38:39], v[38:39], v[44:45]
	v_pk_mul_f32 v[42:43], v[36:37], v[48:49]
	v_pk_mul_f32 v[36:37], v[34:35], v[44:45]
	s_and_b64 vcc, exec, s[4:5]
	v_pk_mul_f32 v[44:45], v[32:33], v[48:49]
	s_cbranch_vccnz .LBB0_547
	v_mul_f32_e32 v33, 0x3d372713, v44
	v_mul_f32_e32 v33, v44, v33
	v_fma_f32 v33, v44, v33, v44
	v_mul_f32_e32 v33, 0x3fcc422a, v33
	v_mul_f32_e32 v33, 0xbfb8aa3b, v33
	v_exp_f32_e32 v33, v33
	v_mul_f32_e32 v32, 0x3d372713, v42
	v_mul_f32_e32 v32, v42, v32
	v_mov_b32_e32 v35, v43
	v_add_f32_e32 v33, 1.0, v33
	v_rcp_f32_e32 v34, v33
	v_mul_f32_e32 v33, 0x3d372713, v43
	v_mul_f32_e32 v33, v43, v33
	v_fma_f32 v32, v42, v32, v42
	v_fmac_f32_e32 v35, v35, v33
	v_mul_f32_e32 v32, 0x3fcc422a, v32
	v_mul_f32_e32 v33, 0x3fcc422a, v35
	v_mul_f32_e32 v32, 0xbfb8aa3b, v32
	v_mul_f32_e32 v33, 0xbfb8aa3b, v33
	v_mul_f32_e32 v47, 0x3d372713, v36
	v_exp_f32_e32 v32, v32
	v_exp_f32_e32 v33, v33
	v_mul_f32_e32 v47, v36, v47
	v_fma_f32 v47, v36, v47, v36
	v_mul_f32_e32 v47, 0x3fcc422a, v47
	v_mul_f32_e32 v47, 0xbfb8aa3b, v47
	v_add_f32_e32 v32, 1.0, v32
	v_add_f32_e32 v33, 1.0, v33
	v_exp_f32_e32 v47, v47
	v_rcp_f32_e32 v32, v32
	v_rcp_f32_e32 v33, v33
	v_mul_f32_e32 v35, 0x3d372713, v45
	v_mul_f32_e32 v35, v45, v35
	v_mov_b32_e32 v46, v45
	v_fmac_f32_e32 v46, v46, v35
	v_add_f32_e32 v47, 1.0, v47
	v_mul_f32_e32 v35, 0x3fcc422a, v46
	v_mul_f32_e32 v46, 0x3d372713, v38
	v_rcp_f32_e32 v48, v47
	v_mul_f32_e32 v47, 0x3d372713, v39
	v_pk_mul_f32 v[42:43], v[42:43], v[32:33]
	v_mul_f32_e32 v32, 0x3d372713, v37
	v_mul_f32_e32 v46, v38, v46
	v_mul_f32_e32 v47, v39, v47
	v_mul_f32_e32 v32, v37, v32
	v_fma_f32 v46, v38, v46, v38
	v_fma_f32 v47, v39, v47, v39
	v_fma_f32 v32, v37, v32, v37
	v_mul_f32_e32 v46, 0x3fcc422a, v46
	v_mul_f32_e32 v47, 0x3fcc422a, v47
	v_mul_f32_e32 v32, 0x3fcc422a, v32
	v_mul_f32_e32 v35, 0xbfb8aa3b, v35
	v_mul_f32_e32 v46, 0xbfb8aa3b, v46
	v_mul_f32_e32 v47, 0xbfb8aa3b, v47
	v_mul_f32_e32 v32, 0xbfb8aa3b, v32
	v_exp_f32_e32 v35, v35
	v_exp_f32_e32 v46, v46
	v_exp_f32_e32 v47, v47
	v_exp_f32_e32 v32, v32
	v_add_f32_e32 v35, 1.0, v35
	v_add_f32_e32 v46, 1.0, v46
	v_add_f32_e32 v47, 1.0, v47
	v_add_f32_e32 v32, 1.0, v32
	v_rcp_f32_e32 v35, v35
	v_rcp_f32_e32 v46, v46
	v_rcp_f32_e32 v47, v47
	v_rcp_f32_e32 v49, v32
	v_pk_mul_f32 v[44:45], v[44:45], v[34:35]
	v_pk_mul_f32 v[38:39], v[38:39], v[46:47]
	v_pk_mul_f32 v[36:37], v[36:37], v[48:49]
.LBB0_547:
	v_mov_b32_e32 v32, v71
	v_mov_b32_e32 v33, v72
	v_mov_b32_e32 v71, v73
	v_mov_b32_e32 v34, v67
	v_mov_b32_e32 v35, v68
	v_mov_b32_e32 v67, v69
	v_pk_add_f32 v[32:33], v[32:33], v[70:71]
	v_pk_add_f32 v[34:35], v[34:35], v[66:67]
	v_mov_b32_e32 v47, v32
	v_mov_b32_e32 v46, v34
	v_mov_b32_e32 v32, v35
	v_pk_add_f32 v[32:33], v[46:47], v[32:33]
	v_cvt_pk_bf16_f32 v42, v42, v43
	v_cvt_pk_bf16_f32 v43, v38, v39
	v_cvt_pk_bf16_f32 v44, v44, v45
	v_cvt_pk_bf16_f32 v45, v36, v37
	global_store_dwordx4 v[40:41], v[42:45], off offset:256 sc1
	v_pk_fma_f32 v[32:33], v[32:33], s[42:43], v[196:197] op_sel_hi:[1,0,0]
	s_nop 0
	v_mul_f32_e32 v34, 0x4b800000, v33
	v_cmp_gt_f32_e32 vcc, s28, v33
	v_cmp_gt_f32_e64 s[6:7], s28, v32
	s_nop 0
	v_cndmask_b32_e32 v33, v33, v34, vcc
	v_rsq_f32_e32 v33, v33
	s_nop 0
	v_mul_f32_e32 v34, 0x45800000, v33
	v_cndmask_b32_e32 v33, v33, v34, vcc
	v_mul_f32_e32 v34, s17, v33
	v_pk_mul_f32 v[30:31], v[30:31], v[34:35] op_sel_hi:[1,0]
	v_pk_mul_f32 v[28:29], v[28:29], v[34:35] op_sel_hi:[1,0]
	v_pk_mul_f32 v[26:27], v[26:27], v[34:35] op_sel_hi:[1,0]
	s_and_b64 vcc, exec, s[4:5]
	v_pk_mul_f32 v[36:37], v[24:25], v[34:35] op_sel_hi:[1,0]
	s_cbranch_vccnz .LBB0_549
	v_mul_f32_e32 v25, 0x3d372713, v36
	v_mul_f32_e32 v25, v36, v25
	v_fma_f32 v25, v36, v25, v36
	v_mul_f32_e32 v25, 0x3fcc422a, v25
	v_mul_f32_e32 v25, 0xbfb8aa3b, v25
	v_exp_f32_e32 v25, v25
	v_mov_b32_e32 v33, v29
	v_mov_b32_e32 v35, v37
	v_mul_f32_e32 v24, 0x3d372713, v28
	v_add_f32_e32 v25, 1.0, v25
	v_rcp_f32_e32 v38, v25
	v_mul_f32_e32 v25, 0x3d372713, v29
	v_mul_f32_e32 v25, v29, v25
	v_fmac_f32_e32 v33, v33, v25
	v_mul_f32_e32 v25, 0x3fcc422a, v33
	v_mul_f32_e32 v33, 0x3d372713, v37
	v_mul_f32_e32 v33, v37, v33
	v_fmac_f32_e32 v35, v35, v33
	v_mul_f32_e32 v33, 0x3fcc422a, v35
	v_mul_f32_e32 v33, 0xbfb8aa3b, v33
	v_exp_f32_e32 v33, v33
	v_mul_f32_e32 v24, v28, v24
	v_fma_f32 v24, v28, v24, v28
	v_mul_f32_e32 v24, 0x3fcc422a, v24
	v_add_f32_e32 v33, 1.0, v33
	v_rcp_f32_e32 v39, v33
	v_mul_f32_e32 v33, 0x3d372713, v30
	v_mul_f32_e32 v33, v30, v33
	v_fma_f32 v33, v30, v33, v30
	v_mul_f32_e32 v33, 0x3fcc422a, v33
	v_mul_f32_e32 v33, 0xbfb8aa3b, v33
	v_exp_f32_e32 v33, v33
	v_mul_f32_e32 v24, 0xbfb8aa3b, v24
	v_mul_f32_e32 v25, 0xbfb8aa3b, v25
	v_exp_f32_e32 v24, v24
	v_add_f32_e32 v33, 1.0, v33
	v_rcp_f32_e32 v40, v33
	v_mul_f32_e32 v33, 0x3d372713, v26
	v_exp_f32_e32 v25, v25
	v_mul_f32_e32 v33, v26, v33
	v_fma_f32 v33, v26, v33, v26
	v_mul_f32_e32 v33, 0x3fcc422a, v33
	v_mul_f32_e32 v33, 0xbfb8aa3b, v33
	v_add_f32_e32 v24, 1.0, v24
	v_add_f32_e32 v25, 1.0, v25
	v_exp_f32_e32 v33, v33
	v_rcp_f32_e32 v24, v24
	v_rcp_f32_e32 v25, v25
	v_pk_mul_f32 v[36:37], v[36:37], v[38:39]
	v_add_f32_e32 v33, 1.0, v33
	v_rcp_f32_e32 v42, v33
	v_mul_f32_e32 v33, 0x3d372713, v31
	v_pk_mul_f32 v[28:29], v[28:29], v[24:25]
	v_mul_f32_e32 v24, 0x3d372713, v27
	v_mul_f32_e32 v33, v31, v33
	v_mul_f32_e32 v24, v27, v24
	v_fma_f32 v33, v31, v33, v31
	v_fma_f32 v24, v27, v24, v27
	v_mul_f32_e32 v33, 0x3fcc422a, v33
	v_mul_f32_e32 v24, 0x3fcc422a, v24
	v_mul_f32_e32 v33, 0xbfb8aa3b, v33
	v_mul_f32_e32 v24, 0xbfb8aa3b, v24
	v_exp_f32_e32 v33, v33
	v_exp_f32_e32 v24, v24
	v_add_f32_e32 v33, 1.0, v33
	v_add_f32_e32 v24, 1.0, v24
	v_rcp_f32_e32 v41, v33
	v_rcp_f32_e32 v43, v24
	v_pk_mul_f32 v[30:31], v[30:31], v[40:41]
	v_pk_mul_f32 v[26:27], v[26:27], v[42:43]
; __device__ __forceinline__ float fgelu_tanh(float v) { return v * fsig(1.5957691216057308f * (v + 0.044715f * v * v * v)); }
; __device__ __forceinline__ u32x4 pack8(const f32x4 v0, const f32x4 v1) { u32x4 w; w.x = cvt_pk_bf16(v0[0], v0[1]); w.y = cvt_pk_bf16(v0[2], v0[3]); w.z = cvt_pk_bf16(v1[0], v1[1]); w.w = cvt_pk_bf16(v1[2], v1[3]); return w; }
; __device__ __forceinline__ void rstd8(const float* ss, int row0, float sc, float (&rs)[2][4]) {
;     ...
;         for (int m = 0; m < 4; ++m) pa[ai][m] = *(const f32x4*)(ss + (size_t)(row0 + ai * HALF + m * 16) * 4);
; #pragma unroll
;     for (int ai = 0; ai < 2; ++ai)
; #pragma unroll
;         for (int m = 0; m < 4; ++m) { const f32x4 a = pa[ai][m]; rs[ai][m] = rsqrtf(((a[0] + a[1]) + (a[2] + a[3])) * (1.0f / 1024.0f) + 1e-6f) * sc; }
;     __device__ __forceinline__ void operator()(const f32x4 (&acc)[2][2][4][2], const Unit& u, int wr, int wc, int fr, int fq) const {
;     ...
;             for (int m = 0; m < 4; ++m) { const int row = row0 + ai * HALF + m * 16; const float rs = rsv[ai][m];
; #pragma unroll
;                 for (int bj = 0; bj < 2; ++bj) { f32x4 v0 = acc[ai][bj][m][0] * rs, v1 = acc[ai][bj][m][1] * rs;
;                     if (act) {
; #pragma unroll
;                         for (int i = 0; i < 4; ++i) { v0[i] = fgelu_tanh(v0[i]); v1[i] = fgelu_tanh(v1[i]); } }
;                     *(u32x4*)(dst + (size_t)row * ld + col0 + bj * HALF) = pack8(v0, v1); __builtin_amdgcn_sched_barrier(0); } }
.LBB0_549:
	v_mul_lo_u32 v33, s45, v168
	v_mul_lo_u32 v38, s44, v169
	v_mad_u64_u32 v[24:25], s[8:9], s44, v168, 0
	v_add3_u32 v25, v25, v38, v33
	v_lshl_add_u64 v[24:25], v[24:25], 1, v[146:147]
	v_mov_b32_e32 v35, v34
	v_cvt_pk_bf16_f32 v28, v28, v29
	v_cvt_pk_bf16_f32 v29, v30, v31
	v_cvt_pk_bf16_f32 v30, v36, v37
	v_cvt_pk_bf16_f32 v31, v26, v27
	global_store_dwordx4 v[24:25], v[28:31], off sc1
	v_mov_b32_e32 v26, v34
	v_mov_b32_e32 v27, v34
	v_pk_mul_f32 v[22:23], v[22:23], v[26:27]
	v_pk_mul_f32 v[20:21], v[20:21], v[34:35]
	v_pk_mul_f32 v[18:19], v[18:19], v[26:27]
	s_and_b64 vcc, exec, s[4:5]
	v_pk_mul_f32 v[16:17], v[16:17], v[34:35]
	s_cbranch_vccnz .LBB0_551
	v_mul_f32_e32 v27, 0x3d372713, v16
	v_mul_f32_e32 v27, v16, v27
	v_fma_f32 v27, v16, v27, v16
	v_mul_f32_e32 v27, 0x3fcc422a, v27
	v_mul_f32_e32 v27, 0xbfb8aa3b, v27
	v_exp_f32_e32 v27, v27
	v_mul_f32_e32 v26, 0x3d372713, v20
	v_mul_f32_e32 v26, v20, v26
	v_mov_b32_e32 v29, v21
	v_add_f32_e32 v27, 1.0, v27
	v_rcp_f32_e32 v28, v27
	v_mul_f32_e32 v27, 0x3d372713, v21
	v_mul_f32_e32 v27, v21, v27
	v_fma_f32 v26, v20, v26, v20
	v_fmac_f32_e32 v29, v29, v27
	v_mul_f32_e32 v26, 0x3fcc422a, v26
	v_mul_f32_e32 v27, 0x3fcc422a, v29
	v_mul_f32_e32 v26, 0xbfb8aa3b, v26
	v_mul_f32_e32 v27, 0xbfb8aa3b, v27
	v_mul_f32_e32 v31, 0x3d372713, v18
	v_exp_f32_e32 v26, v26
	v_exp_f32_e32 v27, v27
	v_mul_f32_e32 v31, v18, v31
	v_fma_f32 v31, v18, v31, v18
	v_mul_f32_e32 v31, 0x3fcc422a, v31
	v_mul_f32_e32 v31, 0xbfb8aa3b, v31
	v_add_f32_e32 v26, 1.0, v26
	v_add_f32_e32 v27, 1.0, v27
	v_exp_f32_e32 v31, v31
	v_rcp_f32_e32 v26, v26
	v_rcp_f32_e32 v27, v27
	v_mul_f32_e32 v29, 0x3d372713, v17
	v_mul_f32_e32 v29, v17, v29
	v_mov_b32_e32 v30, v17
	v_fmac_f32_e32 v30, v30, v29
	v_add_f32_e32 v31, 1.0, v31
	v_mul_f32_e32 v29, 0x3fcc422a, v30
	v_mul_f32_e32 v30, 0x3d372713, v22
	v_rcp_f32_e32 v34, v31
	v_mul_f32_e32 v31, 0x3d372713, v23
	v_pk_mul_f32 v[20:21], v[20:21], v[26:27]
	v_mul_f32_e32 v26, 0x3d372713, v19
	v_mul_f32_e32 v30, v22, v30
	v_mul_f32_e32 v31, v23, v31
	v_mul_f32_e32 v26, v19, v26
	v_fma_f32 v30, v22, v30, v22
	v_fma_f32 v31, v23, v31, v23
	v_fma_f32 v26, v19, v26, v19
	v_mul_f32_e32 v30, 0x3fcc422a, v30
	v_mul_f32_e32 v31, 0x3fcc422a, v31
	v_mul_f32_e32 v26, 0x3fcc422a, v26
	v_mul_f32_e32 v29, 0xbfb8aa3b, v29
	v_mul_f32_e32 v30, 0xbfb8aa3b, v30
	v_mul_f32_e32 v31, 0xbfb8aa3b, v31
	v_mul_f32_e32 v26, 0xbfb8aa3b, v26
	v_exp_f32_e32 v29, v29
	v_exp_f32_e32 v30, v30
	v_exp_f32_e32 v31, v31
	v_exp_f32_e32 v26, v26
	v_add_f32_e32 v29, 1.0, v29
	v_add_f32_e32 v30, 1.0, v30
	v_add_f32_e32 v31, 1.0, v31
	v_add_f32_e32 v26, 1.0, v26
	v_rcp_f32_e32 v29, v29
	v_rcp_f32_e32 v30, v30
	v_rcp_f32_e32 v31, v31
	v_rcp_f32_e32 v35, v26
	v_pk_mul_f32 v[16:17], v[16:17], v[28:29]
	v_pk_mul_f32 v[22:23], v[22:23], v[30:31]
	v_pk_mul_f32 v[18:19], v[18:19], v[34:35]
.LBB0_551:
	v_mul_f32_e32 v26, 0x4b800000, v32
	v_cndmask_b32_e64 v26, v32, v26, s[6:7]
	v_rsq_f32_e32 v26, v26
	v_cvt_pk_bf16_f32 v20, v20, v21
	v_cvt_pk_bf16_f32 v21, v22, v23
	v_cvt_pk_bf16_f32 v22, v16, v17
	v_cvt_pk_bf16_f32 v23, v18, v19
	global_store_dwordx4 v[24:25], v[20:23], off offset:256 sc1
	v_mul_f32_e32 v16, 0x45800000, v26
	v_cndmask_b32_e64 v16, v26, v16, s[6:7]
	v_mul_f32_e32 v16, s17, v16
	v_pk_mul_f32 v[14:15], v[14:15], v[16:17] op_sel_hi:[1,0]
	v_pk_mul_f32 v[12:13], v[12:13], v[16:17] op_sel_hi:[1,0]
	v_pk_mul_f32 v[10:11], v[10:11], v[16:17] op_sel_hi:[1,0]
	s_and_b64 vcc, exec, s[4:5]
	v_pk_mul_f32 v[18:19], v[8:9], v[16:17] op_sel_hi:[1,0]
	s_cbranch_vccnz .LBB0_553
	v_mul_f32_e32 v9, 0x3d372713, v18
	v_mul_f32_e32 v9, v18, v9
	v_fma_f32 v9, v18, v9, v18
	v_mul_f32_e32 v9, 0x3fcc422a, v9
	v_mul_f32_e32 v9, 0xbfb8aa3b, v9
	v_exp_f32_e32 v9, v9
	v_mov_b32_e32 v17, v13
	v_mov_b32_e32 v21, v19
	v_mul_f32_e32 v8, 0x3d372713, v12
	v_add_f32_e32 v9, 1.0, v9
	v_rcp_f32_e32 v20, v9
	v_mul_f32_e32 v9, 0x3d372713, v13
	v_mul_f32_e32 v9, v13, v9
	v_fmac_f32_e32 v17, v17, v9
	v_mul_f32_e32 v9, 0x3fcc422a, v17
	v_mul_f32_e32 v17, 0x3d372713, v19
	v_mul_f32_e32 v17, v19, v17
	v_fmac_f32_e32 v21, v21, v17
	v_mul_f32_e32 v17, 0x3fcc422a, v21
	v_mul_f32_e32 v17, 0xbfb8aa3b, v17
	v_exp_f32_e32 v17, v17
	v_mul_f32_e32 v8, v12, v8
	v_fma_f32 v8, v12, v8, v12
	v_mul_f32_e32 v8, 0x3fcc422a, v8
	v_add_f32_e32 v17, 1.0, v17
	v_rcp_f32_e32 v21, v17
	v_mul_f32_e32 v17, 0x3d372713, v14
	v_mul_f32_e32 v17, v14, v17
	v_fma_f32 v17, v14, v17, v14
	v_mul_f32_e32 v17, 0x3fcc422a, v17
	v_mul_f32_e32 v17, 0xbfb8aa3b, v17
	v_exp_f32_e32 v17, v17
	v_mul_f32_e32 v8, 0xbfb8aa3b, v8
	v_mul_f32_e32 v9, 0xbfb8aa3b, v9
	v_exp_f32_e32 v8, v8
	v_add_f32_e32 v17, 1.0, v17
	v_rcp_f32_e32 v22, v17
	v_mul_f32_e32 v17, 0x3d372713, v10
	v_exp_f32_e32 v9, v9
	v_mul_f32_e32 v17, v10, v17
	v_fma_f32 v17, v10, v17, v10
	v_mul_f32_e32 v17, 0x3fcc422a, v17
	v_mul_f32_e32 v17, 0xbfb8aa3b, v17
	v_add_f32_e32 v8, 1.0, v8
	v_add_f32_e32 v9, 1.0, v9
	v_exp_f32_e32 v17, v17
	v_rcp_f32_e32 v8, v8
	v_rcp_f32_e32 v9, v9
	v_pk_mul_f32 v[18:19], v[18:19], v[20:21]
	v_add_f32_e32 v17, 1.0, v17
	v_rcp_f32_e32 v24, v17
	v_mul_f32_e32 v17, 0x3d372713, v15
	v_pk_mul_f32 v[12:13], v[12:13], v[8:9]
	v_mul_f32_e32 v8, 0x3d372713, v11
	v_mul_f32_e32 v17, v15, v17
	v_mul_f32_e32 v8, v11, v8
	v_fma_f32 v17, v15, v17, v15
	v_fma_f32 v8, v11, v8, v11
	v_mul_f32_e32 v17, 0x3fcc422a, v17
	v_mul_f32_e32 v8, 0x3fcc422a, v8
	v_mul_f32_e32 v17, 0xbfb8aa3b, v17
	v_mul_f32_e32 v8, 0xbfb8aa3b, v8
	v_exp_f32_e32 v17, v17
	v_exp_f32_e32 v8, v8
	v_add_f32_e32 v17, 1.0, v17
	v_add_f32_e32 v8, 1.0, v8
	v_rcp_f32_e32 v23, v17
	v_rcp_f32_e32 v25, v8
	v_pk_mul_f32 v[14:15], v[14:15], v[22:23]
	v_pk_mul_f32 v[10:11], v[10:11], v[24:25]
; __device__ __forceinline__ float fgelu_tanh(float v) { return v * fsig(1.5957691216057308f * (v + 0.044715f * v * v * v)); }
; __device__ __forceinline__ u32x4 pack8(const f32x4 v0, const f32x4 v1) { u32x4 w; w.x = cvt_pk_bf16(v0[0], v0[1]); w.y = cvt_pk_bf16(v0[2], v0[3]); w.z = cvt_pk_bf16(v1[0], v1[1]); w.w = cvt_pk_bf16(v1[2], v1[3]); return w; }
; #define PG8_BAR __builtin_amdgcn_s_barrier()
;     __device__ __forceinline__ void operator()(const f32x4 (&acc)[2][2][4][2], const Unit& u, int wr, int wc, int fr, int fq) const {
;     ...
;             for (int m = 0; m < 4; ++m) { const int row = row0 + ai * HALF + m * 16; const float rs = rsv[ai][m];
; #pragma unroll
;                 for (int bj = 0; bj < 2; ++bj) { f32x4 v0 = acc[ai][bj][m][0] * rs, v1 = acc[ai][bj][m][1] * rs;
;                     if (act) {
; #pragma unroll
;                         for (int i = 0; i < 4; ++i) { v0[i] = fgelu_tanh(v0[i]); v1[i] = fgelu_tanh(v1[i]); } }
;                     *(u32x4*)(dst + (size_t)row * ld + col0 + bj * HALF) = pack8(v0, v1); __builtin_amdgcn_sched_barrier(0); } }
; template <class Epi, class Sched, bool ALIGN_EPI = false, bool SP2 = false>
; __device__ __forceinline__ void gemm_phase(PG8_LAS unsigned char* lds, const Gemm g, const Sched& S, const Epi& E) {
;     ...
;         if constexpr (!Epi::AFTER_DRAIN) { E(acc, cur, wr, wc, fr, fq); S.done(cur); }
;         if (!has_next) break;
; #pragma unroll
;         for (int a = 0; a < 2; ++a)
; #pragma unroll
;             for (int b = 0; b < 2; ++b)
; #pragma unroll
;                 for (int m = 0; m < 4; ++m)
; #pragma unroll
;                     for (int n = 0; n < 2; ++n) acc[a][b][m][n] = (f32x4){0.f, 0.f, 0.f, 0.f};
;         cur = nxt; cA = nA; cB = nB; ++ui;
;         if constexpr (ALIGN_EPI) { if (wr == 1) PG8_BAR; }
;     }
.LBB0_553:
	v_mul_lo_u32 v20, s45, v166
	v_mul_lo_u32 v21, s44, v167
	v_mad_u64_u32 v[8:9], s[6:7], s44, v166, 0
	v_add3_u32 v9, v9, v21, v20
	v_lshl_add_u64 v[8:9], v[8:9], 1, v[146:147]
	v_mov_b32_e32 v17, v16
	v_cvt_pk_bf16_f32 v12, v12, v13
	v_cvt_pk_bf16_f32 v13, v14, v15
	v_cvt_pk_bf16_f32 v14, v18, v19
	v_cvt_pk_bf16_f32 v15, v10, v11
	global_store_dwordx4 v[8:9], v[12:15], off sc1
	v_mov_b32_e32 v10, v16
	v_mov_b32_e32 v11, v16
	v_pk_mul_f32 v[6:7], v[6:7], v[10:11]
	v_pk_mul_f32 v[4:5], v[4:5], v[16:17]
	v_pk_mul_f32 v[2:3], v[2:3], v[10:11]
	s_and_b64 vcc, exec, s[4:5]
	v_pk_mul_f32 v[0:1], v[0:1], v[16:17]
	s_cbranch_vccnz .LBB0_555
	v_mul_f32_e32 v11, 0x3d372713, v0
	v_mul_f32_e32 v11, v0, v11
	v_fma_f32 v11, v0, v11, v0
	v_mul_f32_e32 v11, 0x3fcc422a, v11
	v_mul_f32_e32 v11, 0xbfb8aa3b, v11
	v_exp_f32_e32 v11, v11
	v_mul_f32_e32 v10, 0x3d372713, v4
	v_mul_f32_e32 v10, v4, v10
	v_mov_b32_e32 v13, v5
	v_add_f32_e32 v11, 1.0, v11
	v_rcp_f32_e32 v12, v11
	v_mul_f32_e32 v11, 0x3d372713, v5
	v_mul_f32_e32 v11, v5, v11
	v_fma_f32 v10, v4, v10, v4
	v_fmac_f32_e32 v13, v13, v11
	v_mul_f32_e32 v10, 0x3fcc422a, v10
	v_mul_f32_e32 v11, 0x3fcc422a, v13
	v_mul_f32_e32 v10, 0xbfb8aa3b, v10
	v_mul_f32_e32 v11, 0xbfb8aa3b, v11
	v_mul_f32_e32 v15, 0x3d372713, v2
	v_exp_f32_e32 v10, v10
	v_exp_f32_e32 v11, v11
	v_mul_f32_e32 v15, v2, v15
	v_fma_f32 v15, v2, v15, v2
	v_mul_f32_e32 v15, 0x3fcc422a, v15
	v_mul_f32_e32 v15, 0xbfb8aa3b, v15
	v_add_f32_e32 v10, 1.0, v10
	v_add_f32_e32 v11, 1.0, v11
	v_exp_f32_e32 v15, v15
	v_rcp_f32_e32 v10, v10
	v_rcp_f32_e32 v11, v11
	v_mul_f32_e32 v13, 0x3d372713, v1
	v_mul_f32_e32 v13, v1, v13
	v_mov_b32_e32 v14, v1
	v_fmac_f32_e32 v14, v14, v13
	v_add_f32_e32 v15, 1.0, v15
	v_mul_f32_e32 v13, 0x3fcc422a, v14
	v_mul_f32_e32 v14, 0x3d372713, v6
	v_rcp_f32_e32 v16, v15
	v_mul_f32_e32 v15, 0x3d372713, v7
	v_pk_mul_f32 v[4:5], v[4:5], v[10:11]
	v_mul_f32_e32 v10, 0x3d372713, v3
	v_mul_f32_e32 v14, v6, v14
	v_mul_f32_e32 v15, v7, v15
	v_mul_f32_e32 v10, v3, v10
	v_fma_f32 v14, v6, v14, v6
	v_fma_f32 v15, v7, v15, v7
	v_fma_f32 v10, v3, v10, v3
	v_mul_f32_e32 v14, 0x3fcc422a, v14
	v_mul_f32_e32 v15, 0x3fcc422a, v15
	v_mul_f32_e32 v10, 0x3fcc422a, v10
	v_mul_f32_e32 v13, 0xbfb8aa3b, v13
	v_mul_f32_e32 v14, 0xbfb8aa3b, v14
	v_mul_f32_e32 v15, 0xbfb8aa3b, v15
	v_mul_f32_e32 v10, 0xbfb8aa3b, v10
	v_exp_f32_e32 v13, v13
	v_exp_f32_e32 v14, v14
	v_exp_f32_e32 v15, v15
	v_exp_f32_e32 v10, v10
	v_add_f32_e32 v13, 1.0, v13
	v_add_f32_e32 v14, 1.0, v14
	v_add_f32_e32 v15, 1.0, v15
	v_add_f32_e32 v10, 1.0, v10
	v_rcp_f32_e32 v13, v13
	v_rcp_f32_e32 v14, v14
	v_rcp_f32_e32 v15, v15
	v_rcp_f32_e32 v17, v10
	v_pk_mul_f32 v[0:1], v[0:1], v[12:13]
	v_pk_mul_f32 v[6:7], v[6:7], v[14:15]
	v_pk_mul_f32 v[2:3], v[2:3], v[16:17]
.LBB0_555:
	v_cvt_pk_bf16_f32 v4, v4, v5
	v_cvt_pk_bf16_f32 v5, v6, v7
	v_cvt_pk_bf16_f32 v6, v0, v1
	s_nop 0
	v_cvt_pk_bf16_f32 v7, v2, v3
	global_store_dwordx4 v[8:9], v[4:7], off offset:256 sc1
	s_andn2_b64 vcc, exec, s[2:3]
	s_mov_b64 s[2:3], -1
	s_cbranch_vccnz .LBB0_494
	s_andn2_b64 vcc, exec, s[0:1]
	s_cbranch_vccnz .LBB0_493
	s_barrier
	s_branch .LBB0_493
